# v71 + P4 mlstm_out: wave-0 gate-row loads and wave-1 normaliser loads issued at the unit top by all waves (first barrier of each unit no longer waits for wave 0's load latency)
# baseline (speedup 1.0000x reference)
.LBB0_1049:
	s_or_b32 s33, s24, s72
	s_lshl_b32 s0, s33, 7
	s_or_b32 s68, s18, s0
	s_or_b32 s0, s33, s28
	s_ashr_i32 s1, s0, 31
	s_lshl_b64 s[0:1], s[0:1], 2
	s_add_u32 s0, s73, s0
	s_addc_u32 s1, s74, s1
	v_mov_b32_e32 v4, v0
	global_load_dword v211, v3, s[0:1]
	s_mov_b32 s69, s19
	v_and_b32_e32 v222, 63, v4
	v_lshl_or_b32 v224, v222, 1, s68
	v_mov_b32_e32 v225, s69
	v_lshlrev_b64 v[224:225], 5, v[224:225]
	v_lshl_add_u64 v[224:225], s[64:65], 0, v[224:225]
	global_load_dword v226, v[224:225], off offset:48
	global_load_dword v227, v[224:225], off offset:16
	global_load_dword v228, v[224:225], off offset:32
	global_load_dword v229, v[224:225], off
	s_or_b32 s0, s33, s29
	s_ashr_i32 s1, s0, 31
	s_lshl_b64 s[0:1], s[0:1], 10
	s_add_u32 s0, s77, s0
	s_addc_u32 s1, s78, s1
	v_lshlrev_b32_e32 v223, 2, v222
	global_load_dword v230, v223, s[0:1]
	global_load_dword v231, v223, s[0:1] offset:256
	global_load_dword v232, v223, s[0:1] offset:512
	global_load_dword v233, v223, s[0:1] offset:768
	s_waitcnt vmcnt(17)
	v_ashrrev_i32_e32 v70, 5, v4
	v_ashrrev_i32_e32 v71, 31, v70
	v_lshlrev_b32_e32 v2, 4, v4
	v_lshl_add_u64 v[6:7], s[68:69], 0, v[70:71]
	v_and_b32_e32 v2, 0x1f0, v2
	v_lshl_add_u64 v[8:9], s[20:21], 0, v[2:3]
	v_lshlrev_b64 v[6:7], 11, v[6:7]
	v_lshl_add_u64 v[62:63], v[8:9], 0, v[6:7]
	v_lshl_add_u64 v[10:11], s[36:37], 0, v[2:3]
	v_add_co_u32_e32 v14, vcc, s80, v62
	v_lshl_add_u64 v[64:65], v[10:11], 0, v[6:7]
	s_nop 0
	v_addc_co_u32_e32 v15, vcc, 0, v63, vcc
	v_add_co_u32_e32 v18, vcc, s80, v64
	global_load_dwordx4 v[6:9], v[62:63], off
	global_load_dwordx4 v[10:13], v[64:65], off
	v_addc_co_u32_e32 v19, vcc, 0, v65, vcc
	v_add_co_u32_e32 v22, vcc, s46, v62
	global_load_dwordx4 v[14:17], v[14:15], off
	s_nop 0
	global_load_dwordx4 v[18:21], v[18:19], off
	v_addc_co_u32_e32 v23, vcc, 0, v63, vcc
	v_add_co_u32_e32 v26, vcc, s46, v64
	s_movk_i32 s0, 0x210
	s_nop 0
	v_addc_co_u32_e32 v27, vcc, 0, v65, vcc
	v_add_co_u32_e32 v30, vcc, s81, v62
	global_load_dwordx4 v[22:25], v[22:23], off
	s_nop 0
	global_load_dwordx4 v[26:29], v[26:27], off
	v_addc_co_u32_e32 v31, vcc, 0, v63, vcc
	v_add_co_u32_e32 v34, vcc, s81, v64
	v_mul_lo_u32 v5, v70, s0
	s_nop 0
	v_addc_co_u32_e32 v35, vcc, 0, v65, vcc
	v_add_co_u32_e32 v38, vcc, s47, v62
	global_load_dwordx4 v[30:33], v[30:31], off
	s_nop 0
	global_load_dwordx4 v[34:37], v[34:35], off
	v_addc_co_u32_e32 v39, vcc, 0, v63, vcc
	v_add_co_u32_e32 v42, vcc, s47, v64
	v_add3_u32 v2, v5, v2, 0
	s_nop 0
	v_addc_co_u32_e32 v43, vcc, 0, v65, vcc
	v_add_co_u32_e32 v46, vcc, s82, v62
	global_load_dwordx4 v[38:41], v[38:39], off
	s_nop 0
	global_load_dwordx4 v[42:45], v[42:43], off
	v_addc_co_u32_e32 v47, vcc, 0, v63, vcc
	v_add_co_u32_e32 v50, vcc, s82, v64
	v_add_u32_e32 v5, 0x10800, v2
	s_nop 0
	v_addc_co_u32_e32 v51, vcc, 0, v65, vcc
	v_add_co_u32_e32 v54, vcc, s83, v62
	global_load_dwordx4 v[46:49], v[46:47], off
	s_nop 0
	global_load_dwordx4 v[50:53], v[50:51], off
	v_addc_co_u32_e32 v55, vcc, 0, v63, vcc
	v_add_co_u32_e32 v58, vcc, s83, v64
	s_cmp_lg_u32 s33, 0
	s_nop 0
	v_addc_co_u32_e32 v59, vcc, 0, v65, vcc
	v_add_co_u32_e32 v62, vcc, s84, v62
	global_load_dwordx4 v[54:57], v[54:55], off
	s_nop 0
	global_load_dwordx4 v[58:61], v[58:59], off
	v_addc_co_u32_e32 v63, vcc, 0, v63, vcc
	v_add_co_u32_e32 v66, vcc, s84, v64
	s_cselect_b64 s[24:25], -1, 0
	s_nop 0
	v_addc_co_u32_e32 v67, vcc, 0, v65, vcc
	global_load_dwordx4 v[62:65], v[62:63], off
	s_nop 0
	global_load_dwordx4 v[66:69], v[66:67], off
	s_cmp_eq_u32 s33, 0
	s_cbranch_scc1 .Lmy_p4_noct
	s_or_b32 s0, s33, s29
	s_ashr_i32 s1, s0, 31
	s_lshl_b64 s[0:1], s[0:1], 17
	s_add_u32 s0, s75, s0
	s_addc_u32 s1, s76, s1
	v_and_b32_e32 v216, 63, v4
	v_lshlrev_b32_e32 v216, 4, v216
	v_mov_b32_e32 v217, 0
	v_lshl_add_u64 v[218:219], s[0:1], 0, v[216:217]
	v_lshl_add_u64 v[218:219], v[218:219], 0, s[38:39]
	s_movk_i32 s0, 0x1000
	v_add_co_u32_e32 v220, vcc, s0, v218
	global_load_dwordx4 v[84:87], v[218:219], off
	global_load_dwordx4 v[88:91], v[218:219], off offset:1024
	global_load_dwordx4 v[92:95], v[218:219], off offset:2048
	global_load_dwordx4 v[96:99], v[218:219], off offset:3072
	v_addc_co_u32_e32 v221, vcc, 0, v219, vcc
	global_load_dwordx4 v[100:103], v[220:221], off
	global_load_dwordx4 v[104:107], v[220:221], off offset:1024
	global_load_dwordx4 v[108:111], v[220:221], off offset:2048
	global_load_dwordx4 v[112:115], v[220:221], off offset:3072
	v_add_co_u32_e32 v220, vcc, 0x2000, v218
	s_nop 1
	v_addc_co_u32_e32 v221, vcc, 0, v219, vcc
	v_add_co_u32_e32 v218, vcc, 0x3000, v218
	global_load_dwordx4 v[116:119], v[220:221], off
	global_load_dwordx4 v[120:123], v[220:221], off offset:1024
	global_load_dwordx4 v[124:127], v[220:221], off offset:2048
	global_load_dwordx4 v[128:131], v[220:221], off offset:3072
	v_addc_co_u32_e32 v219, vcc, 0, v219, vcc
	global_load_dwordx4 v[132:135], v[218:219], off
	global_load_dwordx4 v[136:139], v[218:219], off offset:1024
	global_load_dwordx4 v[140:143], v[218:219], off offset:2048
	global_load_dwordx4 v[144:147], v[218:219], off offset:3072

.LBB0_1057:
	v_lshl_or_b32 v6, v5, 1, s68
	v_mov_b32_e32 v7, s69
	v_lshlrev_b64 v[6:7], 5, v[6:7]
	v_lshl_add_u64 v[6:7], s[64:65], 0, v[6:7]
	v_mov_b32_e32 v2, v226
	v_mov_b32_e32 v10, v227
	v_mov_b32_e32 v9, v228
	v_mov_b32_e32 v8, v229
	v_and_b32_e32 v6, 64, v196
	v_add_u32_e32 v7, -1, v196
	v_cmp_lt_i32_e32 vcc, v7, v6
	v_add_u32_e32 v12, -2, v196
	v_add_u32_e32 v13, -4, v196
	v_cndmask_b32_e32 v7, v7, v196, vcc
	v_lshlrev_b32_e32 v11, 2, v7
	v_cmp_lt_i32_e32 vcc, v12, v6
	v_cmp_lt_i32_e64 s[0:1], v13, v6
	v_cmp_gt_u32_e64 s[4:5], 2, v5
	v_cndmask_b32_e32 v12, v12, v196, vcc
	v_cmp_eq_u32_e32 vcc, 0, v5
	v_lshlrev_b32_e32 v12, 2, v12
	v_cndmask_b32_e64 v13, v13, v196, s[0:1]
	v_lshlrev_b32_e32 v13, 2, v13
	v_add_u32_e32 v14, -8, v196
	v_cmp_lt_i32_e64 s[0:1], v14, v6
	v_add_u32_e32 v15, -16, v196
	v_cmp_lt_i32_e64 s[6:7], v15, v6
	v_cndmask_b32_e64 v14, v14, v196, s[0:1]
	v_cmp_gt_u32_e64 s[0:1], 4, v5
	v_lshlrev_b32_e32 v14, 2, v14
	v_cndmask_b32_e64 v15, v15, v196, s[6:7]
	v_cmp_gt_u32_e64 s[6:7], 8, v5
	v_lshlrev_b32_e32 v15, 2, v15
	v_subrev_u32_e32 v16, 32, v196
	v_cmp_lt_i32_e64 s[8:9], v16, v6
	v_cmp_gt_u32_e64 s[10:11], 32, v5
	v_add_f32_e32 v7, v10, v2
	ds_bpermute_b32 v10, v11, v7
	v_cndmask_b32_e64 v6, v16, v196, s[8:9]
	v_lshlrev_b32_e32 v16, 2, v6
	v_cmp_gt_u32_e64 s[8:9], 16, v5
	s_waitcnt lgkmcnt(0)
	v_add_f32_e32 v10, v7, v10
	v_cndmask_b32_e32 v7, v10, v7, vcc
	ds_bpermute_b32 v10, v12, v7
	s_waitcnt lgkmcnt(0)
	v_add_f32_e32 v10, v7, v10
	v_cndmask_b32_e64 v7, v10, v7, s[4:5]
	ds_bpermute_b32 v10, v13, v7
	s_waitcnt lgkmcnt(0)
	v_add_f32_e32 v10, v7, v10
	v_cndmask_b32_e64 v7, v10, v7, s[0:1]
	ds_bpermute_b32 v10, v14, v7
	s_waitcnt lgkmcnt(0)
	v_add_f32_e32 v10, v7, v10
	v_cndmask_b32_e64 v7, v10, v7, s[6:7]
	ds_bpermute_b32 v10, v15, v7
	s_waitcnt lgkmcnt(0)
	v_add_f32_e32 v6, v7, v10
	v_cndmask_b32_e64 v6, v6, v7, s[8:9]
	ds_bpermute_b32 v7, v16, v6
	s_waitcnt lgkmcnt(0)
	v_add_f32_e32 v7, v6, v7
	v_cndmask_b32_e64 v7, v7, v6, s[10:11]
	v_sub_f32_e32 v6, v7, v2
	v_pk_add_f32 v[8:9], v[8:9], v[6:7] neg_lo:[0,1] neg_hi:[0,1]
	s_nop 0
	v_max_f32_e32 v2, v8, v9
	ds_bpermute_b32 v10, v11, v2
	s_waitcnt lgkmcnt(0)
	v_max_f32_e32 v10, v10, v10
	v_max_f32_e32 v10, v2, v10
	v_cndmask_b32_e32 v2, v10, v2, vcc
	ds_bpermute_b32 v10, v12, v2
	v_lshl_add_u32 v12, v5, 3, 0
	s_waitcnt lgkmcnt(0)
	v_max_f32_e32 v10, v10, v10
	v_max_f32_e32 v10, v2, v10
	v_cndmask_b32_e64 v2, v10, v2, s[4:5]
	ds_bpermute_b32 v10, v13, v2
	v_max_f32_e32 v13, v211, v211
	s_waitcnt lgkmcnt(0)
	v_max_f32_e32 v10, v10, v10
	v_max_f32_e32 v10, v2, v10
	v_cndmask_b32_e64 v2, v10, v2, s[0:1]
	ds_bpermute_b32 v10, v14, v2
	s_waitcnt lgkmcnt(0)
	v_max_f32_e32 v10, v10, v10
	v_max_f32_e32 v10, v2, v10
	v_cndmask_b32_e64 v2, v10, v2, s[6:7]
	ds_bpermute_b32 v10, v15, v2
	s_waitcnt lgkmcnt(0)
	v_max_f32_e32 v10, v10, v10
	v_max_f32_e32 v10, v2, v10
	v_cndmask_b32_e64 v2, v10, v2, s[8:9]
	ds_bpermute_b32 v10, v16, v2
	v_max_f32_e32 v14, v2, v2
	s_waitcnt lgkmcnt(0)
	v_max_f32_e32 v10, v10, v10
	v_max_f32_e32 v10, v14, v10
	v_cndmask_b32_e64 v2, v10, v2, s[10:11]
	ds_bpermute_b32 v2, v11, v2
	v_add_u32_e32 v10, 0x21000, v12
	ds_write_b64 v10, v[8:9]
	v_add_u32_e32 v11, 0x21200, v12
	v_add_u32_e32 v12, 0x21400, v12
	s_waitcnt lgkmcnt(1)
	v_cndmask_b32_e32 v2, v2, v210, vcc
	v_max_f32_e32 v2, v2, v2
	v_max_f32_e32 v2, v2, v8
	v_max_f32_e32 v8, v2, v13
	v_max3_f32 v9, v2, v9, v211
	v_pk_add_f32 v[6:7], v[6:7], v[8:9]
	ds_write_b64 v11, v[8:9]
	ds_write_b64 v12, v[6:7]
	s_andn2_b64 vcc, exec, s[90:91]
	s_cbranch_vccnz .LBB0_1053
.LBB0_1058:
	s_or_b32 s0, s33, s29
	s_ashr_i32 s1, s0, 31
	s_lshl_b64 s[0:1], s[0:1], 10
	s_add_u32 s0, s77, s0
	s_addc_u32 s1, s78, s1
	v_lshlrev_b32_e32 v2, 2, v5
	v_mov_b32_e32 v6, v230
	v_mov_b32_e32 v7, v231
	v_mov_b32_e32 v8, v232
	s_nop 0
	v_mov_b32_e32 v2, v233
	v_lshl_add_u32 v5, v5, 1, 0
	v_add_u32_e32 v5, 0x21700, v5
	v_cvt_pk_bf16_f32 v6, v6, s0
	v_cvt_pk_bf16_f32 v7, v7, s0
	v_cvt_pk_bf16_f32 v8, v8, s0
	v_cvt_pk_bf16_f32 v2, v2, s0
	ds_write_b16 v5, v6
	ds_write_b16 v5, v7 offset:128
	ds_write_b16 v5, v8 offset:256
	ds_write_b16 v5, v2 offset:384
	s_movk_i32 s0, 0x80
	v_cmp_gt_i32_e32 vcc, s0, v4
	s_and_saveexec_b64 s[0:1], vcc
	s_cbranch_execnz .LBB0_1054
	s_branch .LBB0_1055
